# combined: flat XCD-local barrier release + V^T transpose stores through LDS + NA/GQA bias-LUT refill skipped for repeated head/group, on top of the peeled-iteration kernel
# speedup vs baseline: 1.0023x; 1.0023x over previous
; __device__ __forceinline__ unsigned pk2(float lo, float hi) { return pg8::cvt_pk_bf16(lo, hi); }
;     __device__ __forceinline__ void operator()(const pg8::f32x4 (&acc)[2][2][4][2], const pg8::Unit& u, int wr, int wc, int fr, int fq) const {
;     ...
;                         const pg8::f32x4 v0 = acc[ai][bj][m][0] * rs, v1 = acc[ai][bj][m][1] * rs;
;                         u32x4 w; w.x = pk2(v0[0], v0[1]); w.y = pk2(v0[2], v0[3]); w.z = pk2(v1[0], v1[1]); w.w = pk2(v1[2], v1[3]);
;                         if (vt_all || (vt_half && bj == 1)) {
;                             bf16_t* vp = vt + (size_t)(vrow0 + bj * 128) * S + row;
;                             vp[0 * (size_t)S] = (bf16_t)(w.x & 0xffffu); vp[1 * (size_t)S] = (bf16_t)(w.x >> 16); vp[2 * (size_t)S] = (bf16_t)(w.y & 0xffffu); vp[3 * (size_t)S] = (bf16_t)(w.y >> 16);
;                             vp[4 * (size_t)S] = (bf16_t)(w.z & 0xffffu); vp[5 * (size_t)S] = (bf16_t)(w.z >> 16); vp[6 * (size_t)S] = (bf16_t)(w.w & 0xffffu); vp[7 * (size_t)S] = (bf16_t)(w.w >> 16);
.LBB0_354:
	v_or_b32_e32 v128, s21, v171
	s_andn2_b64 vcc, exec, s[4:5]
	v_ashrrev_i32_e32 v129, 31, v128
	s_cbranch_vccnz .LBB0_356
	ds_write_b128 v226, v[124:127]
	v_lshlrev_b64 v[130:131], 15, v[128:129]
	v_lshl_add_u64 v[130:131], s[6:7], 0, v[130:131]
	v_lshl_add_u64 v[130:131], v[250:251], 1, v[130:131]
	v_lshl_add_u64 v[130:131], v[248:249], 0, v[130:131]
	v_add_co_u32_e32 v140, vcc, 0x8000, v130
	ds_read_b64_tr_b16 v[124:125], v227
	ds_read_b64_tr_b16 v[126:127], v227 offset:128
	s_waitcnt lgkmcnt(0)
	global_store_dwordx4 v[130:131], v[124:127], off
	s_nop 1

; __device__ __forceinline__ unsigned pk2(float lo, float hi) { return pg8::cvt_pk_bf16(lo, hi); }
;     __device__ __forceinline__ void operator()(const pg8::f32x4 (&acc)[2][2][4][2], const pg8::Unit& u, int wr, int wc, int fr, int fq) const {
;     ...
;                         const pg8::f32x4 v0 = acc[ai][bj][m][0] * rs, v1 = acc[ai][bj][m][1] * rs;
;                         u32x4 w; w.x = pk2(v0[0], v0[1]); w.y = pk2(v0[2], v0[3]); w.z = pk2(v1[0], v1[1]); w.w = pk2(v1[2], v1[3]);
;                         if (vt_all || (vt_half && bj == 1)) {
;                             bf16_t* vp = vt + (size_t)(vrow0 + bj * 128) * S + row;
;                             vp[0 * (size_t)S] = (bf16_t)(w.x & 0xffffu); vp[1 * (size_t)S] = (bf16_t)(w.x >> 16); vp[2 * (size_t)S] = (bf16_t)(w.y & 0xffffu); vp[3 * (size_t)S] = (bf16_t)(w.y >> 16);
;                             vp[4 * (size_t)S] = (bf16_t)(w.z & 0xffffu); vp[5 * (size_t)S] = (bf16_t)(w.z >> 16); vp[6 * (size_t)S] = (bf16_t)(w.w & 0xffffu); vp[7 * (size_t)S] = (bf16_t)(w.w >> 16);
.LBB0_363:
	s_and_b64 vcc, exec, s[0:1]
	s_cbranch_vccz .LBB0_365
	ds_write_b128 v226, v[116:119]
	v_lshlrev_b64 v[120:121], 15, v[128:129]
	v_lshl_add_u64 v[120:121], s[6:7], 0, v[120:121]
	v_lshl_add_u64 v[120:121], v[250:251], 1, v[120:121]
	v_lshl_add_u64 v[120:121], v[248:249], 0, v[120:121]
	v_add_co_u32_e32 v122, vcc, 0x400000, v120
	s_nop 1
	v_addc_co_u32_e32 v123, vcc, 0, v121, vcc
	ds_read_b64_tr_b16 v[116:117], v227
	ds_read_b64_tr_b16 v[118:119], v227 offset:128
	s_waitcnt lgkmcnt(0)
	global_store_dwordx4 v[122:123], v[116:119], off
	s_nop 1

; __device__ __forceinline__ unsigned pk2(float lo, float hi) { return pg8::cvt_pk_bf16(lo, hi); }
;     __device__ __forceinline__ void operator()(const pg8::f32x4 (&acc)[2][2][4][2], const pg8::Unit& u, int wr, int wc, int fr, int fq) const {
;     ...
;                         const pg8::f32x4 v0 = acc[ai][bj][m][0] * rs, v1 = acc[ai][bj][m][1] * rs;
;                         u32x4 w; w.x = pk2(v0[0], v0[1]); w.y = pk2(v0[2], v0[3]); w.z = pk2(v1[0], v1[1]); w.w = pk2(v1[2], v1[3]);
;                         if (vt_all || (vt_half && bj == 1)) {
;                             bf16_t* vp = vt + (size_t)(vrow0 + bj * 128) * S + row;
;                             vp[0 * (size_t)S] = (bf16_t)(w.x & 0xffffu); vp[1 * (size_t)S] = (bf16_t)(w.x >> 16); vp[2 * (size_t)S] = (bf16_t)(w.y & 0xffffu); vp[3 * (size_t)S] = (bf16_t)(w.y >> 16);
;                             vp[4 * (size_t)S] = (bf16_t)(w.z & 0xffffu); vp[5 * (size_t)S] = (bf16_t)(w.z >> 16); vp[6 * (size_t)S] = (bf16_t)(w.w & 0xffffu); vp[7 * (size_t)S] = (bf16_t)(w.w >> 16);
.LBB0_374:
	ds_write_b128 v226, v[108:111]
	v_lshlrev_b64 v[112:113], 15, v[128:129]
	v_lshl_add_u64 v[112:113], s[6:7], 0, v[112:113]
	v_lshl_add_u64 v[112:113], v[250:251], 1, v[112:113]
	v_lshl_add_u64 v[112:113], v[248:249], 0, v[112:113]
	v_add_co_u32_e32 v114, vcc, 0x8000, v112
	ds_read_b64_tr_b16 v[108:109], v227
	ds_read_b64_tr_b16 v[110:111], v227 offset:128
	s_waitcnt lgkmcnt(0)
	global_store_dwordx4 v[112:113], v[108:111], off offset:32
	s_nop 1
	v_mov_b32_e32 v119, v118
	s_cmp_lt_i32 s57, 10
	s_cbranch_scc0 .LBB0_372

; __device__ __forceinline__ unsigned pk2(float lo, float hi) { return pg8::cvt_pk_bf16(lo, hi); }
;     __device__ __forceinline__ void operator()(const pg8::f32x4 (&acc)[2][2][4][2], const pg8::Unit& u, int wr, int wc, int fr, int fq) const {
;     ...
;                         const pg8::f32x4 v0 = acc[ai][bj][m][0] * rs, v1 = acc[ai][bj][m][1] * rs;
;                         u32x4 w; w.x = pk2(v0[0], v0[1]); w.y = pk2(v0[2], v0[3]); w.z = pk2(v1[0], v1[1]); w.w = pk2(v1[2], v1[3]);
;                         if (vt_all || (vt_half && bj == 1)) {
;                             bf16_t* vp = vt + (size_t)(vrow0 + bj * 128) * S + row;
;                             vp[0 * (size_t)S] = (bf16_t)(w.x & 0xffffu); vp[1 * (size_t)S] = (bf16_t)(w.x >> 16); vp[2 * (size_t)S] = (bf16_t)(w.y & 0xffffu); vp[3 * (size_t)S] = (bf16_t)(w.y >> 16);
;                             vp[4 * (size_t)S] = (bf16_t)(w.z & 0xffffu); vp[5 * (size_t)S] = (bf16_t)(w.z >> 16); vp[6 * (size_t)S] = (bf16_t)(w.w & 0xffffu); vp[7 * (size_t)S] = (bf16_t)(w.w >> 16);
.LBB0_380:
	s_and_b64 vcc, exec, s[0:1]
	s_cbranch_vccz .LBB0_382
	ds_write_b128 v226, v[100:103]
	v_lshlrev_b64 v[104:105], 15, v[128:129]
	v_lshl_add_u64 v[104:105], s[6:7], 0, v[104:105]
	v_lshl_add_u64 v[104:105], v[250:251], 1, v[104:105]
	v_lshl_add_u64 v[104:105], v[248:249], 0, v[104:105]
	v_add_co_u32_e32 v106, vcc, 0x400000, v104
	s_nop 1
	v_addc_co_u32_e32 v107, vcc, 0, v105, vcc
	ds_read_b64_tr_b16 v[100:101], v227
	ds_read_b64_tr_b16 v[102:103], v227 offset:128
	s_waitcnt lgkmcnt(0)
	global_store_dwordx4 v[106:107], v[100:103], off offset:32
	s_nop 1

; __device__ __forceinline__ unsigned pk2(float lo, float hi) { return pg8::cvt_pk_bf16(lo, hi); }
;     __device__ __forceinline__ void operator()(const pg8::f32x4 (&acc)[2][2][4][2], const pg8::Unit& u, int wr, int wc, int fr, int fq) const {
;     ...
;                         const pg8::f32x4 v0 = acc[ai][bj][m][0] * rs, v1 = acc[ai][bj][m][1] * rs;
;                         u32x4 w; w.x = pk2(v0[0], v0[1]); w.y = pk2(v0[2], v0[3]); w.z = pk2(v1[0], v1[1]); w.w = pk2(v1[2], v1[3]);
;                         if (vt_all || (vt_half && bj == 1)) {
;                             bf16_t* vp = vt + (size_t)(vrow0 + bj * 128) * S + row;
;                             vp[0 * (size_t)S] = (bf16_t)(w.x & 0xffffu); vp[1 * (size_t)S] = (bf16_t)(w.x >> 16); vp[2 * (size_t)S] = (bf16_t)(w.y & 0xffffu); vp[3 * (size_t)S] = (bf16_t)(w.y >> 16);
;                             vp[4 * (size_t)S] = (bf16_t)(w.z & 0xffffu); vp[5 * (size_t)S] = (bf16_t)(w.z >> 16); vp[6 * (size_t)S] = (bf16_t)(w.w & 0xffffu); vp[7 * (size_t)S] = (bf16_t)(w.w >> 16);
.LBB0_391:
	ds_write_b128 v226, v[92:95]
	v_lshlrev_b64 v[96:97], 15, v[128:129]
	v_lshl_add_u64 v[96:97], s[6:7], 0, v[96:97]
	v_lshl_add_u64 v[96:97], v[250:251], 1, v[96:97]
	v_lshl_add_u64 v[96:97], v[248:249], 0, v[96:97]
	v_add_co_u32_e32 v98, vcc, 0x8000, v96
	ds_read_b64_tr_b16 v[92:93], v227
	ds_read_b64_tr_b16 v[94:95], v227 offset:128
	s_waitcnt lgkmcnt(0)
	global_store_dwordx4 v[96:97], v[92:95], off offset:64
	s_nop 1
	v_mov_b32_e32 v103, v102
	s_cmp_lt_i32 s57, 10
	s_cbranch_scc0 .LBB0_389

; __device__ __forceinline__ unsigned pk2(float lo, float hi) { return pg8::cvt_pk_bf16(lo, hi); }
;     __device__ __forceinline__ void operator()(const pg8::f32x4 (&acc)[2][2][4][2], const pg8::Unit& u, int wr, int wc, int fr, int fq) const {
;     ...
;                         const pg8::f32x4 v0 = acc[ai][bj][m][0] * rs, v1 = acc[ai][bj][m][1] * rs;
;                         u32x4 w; w.x = pk2(v0[0], v0[1]); w.y = pk2(v0[2], v0[3]); w.z = pk2(v1[0], v1[1]); w.w = pk2(v1[2], v1[3]);
;                         if (vt_all || (vt_half && bj == 1)) {
;                             bf16_t* vp = vt + (size_t)(vrow0 + bj * 128) * S + row;
;                             vp[0 * (size_t)S] = (bf16_t)(w.x & 0xffffu); vp[1 * (size_t)S] = (bf16_t)(w.x >> 16); vp[2 * (size_t)S] = (bf16_t)(w.y & 0xffffu); vp[3 * (size_t)S] = (bf16_t)(w.y >> 16);
;                             vp[4 * (size_t)S] = (bf16_t)(w.z & 0xffffu); vp[5 * (size_t)S] = (bf16_t)(w.z >> 16); vp[6 * (size_t)S] = (bf16_t)(w.w & 0xffffu); vp[7 * (size_t)S] = (bf16_t)(w.w >> 16);
.LBB0_397:
	s_and_b64 vcc, exec, s[0:1]
	s_cbranch_vccz .LBB0_399
	ds_write_b128 v226, v[84:87]
	v_lshlrev_b64 v[88:89], 15, v[128:129]
	v_lshl_add_u64 v[88:89], s[6:7], 0, v[88:89]
	v_lshl_add_u64 v[88:89], v[250:251], 1, v[88:89]
	v_lshl_add_u64 v[88:89], v[248:249], 0, v[88:89]
	v_add_co_u32_e32 v90, vcc, 0x400000, v88
	s_nop 1
	v_addc_co_u32_e32 v91, vcc, 0, v89, vcc
	ds_read_b64_tr_b16 v[84:85], v227
	ds_read_b64_tr_b16 v[86:87], v227 offset:128
	s_waitcnt lgkmcnt(0)
	global_store_dwordx4 v[90:91], v[84:87], off offset:64
	s_nop 1

; __device__ __forceinline__ unsigned pk2(float lo, float hi) { return pg8::cvt_pk_bf16(lo, hi); }
;     __device__ __forceinline__ void operator()(const pg8::f32x4 (&acc)[2][2][4][2], const pg8::Unit& u, int wr, int wc, int fr, int fq) const {
;     ...
;                         const pg8::f32x4 v0 = acc[ai][bj][m][0] * rs, v1 = acc[ai][bj][m][1] * rs;
;                         u32x4 w; w.x = pk2(v0[0], v0[1]); w.y = pk2(v0[2], v0[3]); w.z = pk2(v1[0], v1[1]); w.w = pk2(v1[2], v1[3]);
;                         if (vt_all || (vt_half && bj == 1)) {
;                             bf16_t* vp = vt + (size_t)(vrow0 + bj * 128) * S + row;
;                             vp[0 * (size_t)S] = (bf16_t)(w.x & 0xffffu); vp[1 * (size_t)S] = (bf16_t)(w.x >> 16); vp[2 * (size_t)S] = (bf16_t)(w.y & 0xffffu); vp[3 * (size_t)S] = (bf16_t)(w.y >> 16);
;                             vp[4 * (size_t)S] = (bf16_t)(w.z & 0xffffu); vp[5 * (size_t)S] = (bf16_t)(w.z >> 16); vp[6 * (size_t)S] = (bf16_t)(w.w & 0xffffu); vp[7 * (size_t)S] = (bf16_t)(w.w >> 16);
.LBB0_408:
	ds_write_b128 v226, v[76:79]
	v_lshlrev_b64 v[80:81], 15, v[128:129]
	v_lshl_add_u64 v[80:81], s[6:7], 0, v[80:81]
	v_lshl_add_u64 v[80:81], v[250:251], 1, v[80:81]
	v_lshl_add_u64 v[80:81], v[248:249], 0, v[80:81]
	v_add_co_u32_e32 v82, vcc, 0x8000, v80
	ds_read_b64_tr_b16 v[76:77], v227
	ds_read_b64_tr_b16 v[78:79], v227 offset:128
	s_waitcnt lgkmcnt(0)
	global_store_dwordx4 v[80:81], v[76:79], off offset:96
	s_nop 1
	v_mov_b32_e32 v87, v86
	s_cmp_lt_i32 s57, 10
	s_cbranch_scc0 .LBB0_406

; __device__ __forceinline__ unsigned pk2(float lo, float hi) { return pg8::cvt_pk_bf16(lo, hi); }
;     __device__ __forceinline__ void operator()(const pg8::f32x4 (&acc)[2][2][4][2], const pg8::Unit& u, int wr, int wc, int fr, int fq) const {
;     ...
;                         const pg8::f32x4 v0 = acc[ai][bj][m][0] * rs, v1 = acc[ai][bj][m][1] * rs;
;                         u32x4 w; w.x = pk2(v0[0], v0[1]); w.y = pk2(v0[2], v0[3]); w.z = pk2(v1[0], v1[1]); w.w = pk2(v1[2], v1[3]);
;                         if (vt_all || (vt_half && bj == 1)) {
;                             bf16_t* vp = vt + (size_t)(vrow0 + bj * 128) * S + row;
;                             vp[0 * (size_t)S] = (bf16_t)(w.x & 0xffffu); vp[1 * (size_t)S] = (bf16_t)(w.x >> 16); vp[2 * (size_t)S] = (bf16_t)(w.y & 0xffffu); vp[3 * (size_t)S] = (bf16_t)(w.y >> 16);
;                             vp[4 * (size_t)S] = (bf16_t)(w.z & 0xffffu); vp[5 * (size_t)S] = (bf16_t)(w.z >> 16); vp[6 * (size_t)S] = (bf16_t)(w.w & 0xffffu); vp[7 * (size_t)S] = (bf16_t)(w.w >> 16);
.LBB0_414:
	s_and_b64 vcc, exec, s[0:1]
	s_cbranch_vccz .LBB0_416
	ds_write_b128 v226, v[68:71]
	v_lshlrev_b64 v[72:73], 15, v[128:129]
	v_lshl_add_u64 v[72:73], s[6:7], 0, v[72:73]
	v_lshl_add_u64 v[72:73], v[250:251], 1, v[72:73]
	v_lshl_add_u64 v[72:73], v[248:249], 0, v[72:73]
	v_add_co_u32_e32 v74, vcc, 0x400000, v72
	s_nop 1
	v_addc_co_u32_e32 v75, vcc, 0, v73, vcc
	ds_read_b64_tr_b16 v[68:69], v227
	ds_read_b64_tr_b16 v[70:71], v227 offset:128
	s_waitcnt lgkmcnt(0)
	global_store_dwordx4 v[74:75], v[68:71], off offset:96
	s_nop 1

; __device__ __forceinline__ unsigned pk2(float lo, float hi) { return pg8::cvt_pk_bf16(lo, hi); }
;     __device__ __forceinline__ void operator()(const pg8::f32x4 (&acc)[2][2][4][2], const pg8::Unit& u, int wr, int wc, int fr, int fq) const {
;     ...
;                         const pg8::f32x4 v0 = acc[ai][bj][m][0] * rs, v1 = acc[ai][bj][m][1] * rs;
;                         u32x4 w; w.x = pk2(v0[0], v0[1]); w.y = pk2(v0[2], v0[3]); w.z = pk2(v1[0], v1[1]); w.w = pk2(v1[2], v1[3]);
;                         if (vt_all || (vt_half && bj == 1)) {
;                             bf16_t* vp = vt + (size_t)(vrow0 + bj * 128) * S + row;
;                             vp[0 * (size_t)S] = (bf16_t)(w.x & 0xffffu); vp[1 * (size_t)S] = (bf16_t)(w.x >> 16); vp[2 * (size_t)S] = (bf16_t)(w.y & 0xffffu); vp[3 * (size_t)S] = (bf16_t)(w.y >> 16);
;                             vp[4 * (size_t)S] = (bf16_t)(w.z & 0xffffu); vp[5 * (size_t)S] = (bf16_t)(w.z >> 16); vp[6 * (size_t)S] = (bf16_t)(w.w & 0xffffu); vp[7 * (size_t)S] = (bf16_t)(w.w >> 16);
.LBB0_425:
	ds_write_b128 v226, v[60:63]
	v_lshlrev_b64 v[64:65], 15, v[128:129]
	v_lshl_add_u64 v[64:65], s[6:7], 0, v[64:65]
	v_lshl_add_u64 v[64:65], v[250:251], 1, v[64:65]
	v_lshl_add_u64 v[64:65], v[248:249], 0, v[64:65]
	v_add_co_u32_e32 v66, vcc, 0x8000, v64
	ds_read_b64_tr_b16 v[60:61], v227
	ds_read_b64_tr_b16 v[62:63], v227 offset:128
	s_waitcnt lgkmcnt(0)
	global_store_dwordx4 v[64:65], v[60:63], off offset:256
	s_nop 1
	v_mov_b32_e32 v71, v70
	s_cmp_lt_i32 s57, 10
	s_cbranch_scc0 .LBB0_423

; __device__ __forceinline__ unsigned pk2(float lo, float hi) { return pg8::cvt_pk_bf16(lo, hi); }
;     __device__ __forceinline__ void operator()(const pg8::f32x4 (&acc)[2][2][4][2], const pg8::Unit& u, int wr, int wc, int fr, int fq) const {
;     ...
;                         const pg8::f32x4 v0 = acc[ai][bj][m][0] * rs, v1 = acc[ai][bj][m][1] * rs;
;                         u32x4 w; w.x = pk2(v0[0], v0[1]); w.y = pk2(v0[2], v0[3]); w.z = pk2(v1[0], v1[1]); w.w = pk2(v1[2], v1[3]);
;                         if (vt_all || (vt_half && bj == 1)) {
;                             bf16_t* vp = vt + (size_t)(vrow0 + bj * 128) * S + row;
;                             vp[0 * (size_t)S] = (bf16_t)(w.x & 0xffffu); vp[1 * (size_t)S] = (bf16_t)(w.x >> 16); vp[2 * (size_t)S] = (bf16_t)(w.y & 0xffffu); vp[3 * (size_t)S] = (bf16_t)(w.y >> 16);
;                             vp[4 * (size_t)S] = (bf16_t)(w.z & 0xffffu); vp[5 * (size_t)S] = (bf16_t)(w.z >> 16); vp[6 * (size_t)S] = (bf16_t)(w.w & 0xffffu); vp[7 * (size_t)S] = (bf16_t)(w.w >> 16);
.LBB0_431:
	s_and_b64 vcc, exec, s[0:1]
	s_cbranch_vccz .LBB0_433
	ds_write_b128 v226, v[52:55]
	v_lshlrev_b64 v[56:57], 15, v[128:129]
	v_lshl_add_u64 v[56:57], s[6:7], 0, v[56:57]
	v_lshl_add_u64 v[56:57], v[250:251], 1, v[56:57]
	v_lshl_add_u64 v[56:57], v[248:249], 0, v[56:57]
	v_add_co_u32_e32 v58, vcc, 0x400000, v56
	s_nop 1
	v_addc_co_u32_e32 v59, vcc, 0, v57, vcc
	ds_read_b64_tr_b16 v[52:53], v227
	ds_read_b64_tr_b16 v[54:55], v227 offset:128
	s_waitcnt lgkmcnt(0)
	global_store_dwordx4 v[58:59], v[52:55], off offset:256
	s_nop 1

; __device__ __forceinline__ unsigned pk2(float lo, float hi) { return pg8::cvt_pk_bf16(lo, hi); }
;     __device__ __forceinline__ void operator()(const pg8::f32x4 (&acc)[2][2][4][2], const pg8::Unit& u, int wr, int wc, int fr, int fq) const {
;     ...
;                         const pg8::f32x4 v0 = acc[ai][bj][m][0] * rs, v1 = acc[ai][bj][m][1] * rs;
;                         u32x4 w; w.x = pk2(v0[0], v0[1]); w.y = pk2(v0[2], v0[3]); w.z = pk2(v1[0], v1[1]); w.w = pk2(v1[2], v1[3]);
;                         if (vt_all || (vt_half && bj == 1)) {
;                             bf16_t* vp = vt + (size_t)(vrow0 + bj * 128) * S + row;
;                             vp[0 * (size_t)S] = (bf16_t)(w.x & 0xffffu); vp[1 * (size_t)S] = (bf16_t)(w.x >> 16); vp[2 * (size_t)S] = (bf16_t)(w.y & 0xffffu); vp[3 * (size_t)S] = (bf16_t)(w.y >> 16);
;                             vp[4 * (size_t)S] = (bf16_t)(w.z & 0xffffu); vp[5 * (size_t)S] = (bf16_t)(w.z >> 16); vp[6 * (size_t)S] = (bf16_t)(w.w & 0xffffu); vp[7 * (size_t)S] = (bf16_t)(w.w >> 16);
.LBB0_442:
	ds_write_b128 v226, v[44:47]
	v_lshlrev_b64 v[48:49], 15, v[128:129]
	v_lshl_add_u64 v[48:49], s[6:7], 0, v[48:49]
	v_lshl_add_u64 v[48:49], v[250:251], 1, v[48:49]
	v_lshl_add_u64 v[48:49], v[248:249], 0, v[48:49]
	v_add_co_u32_e32 v50, vcc, 0x8000, v48
	ds_read_b64_tr_b16 v[44:45], v227
	ds_read_b64_tr_b16 v[46:47], v227 offset:128
	s_waitcnt lgkmcnt(0)
	global_store_dwordx4 v[48:49], v[44:47], off offset:288
	s_nop 1
	v_mov_b32_e32 v55, v54
	s_cmp_lt_i32 s57, 10
	s_cbranch_scc0 .LBB0_440

; __device__ __forceinline__ unsigned pk2(float lo, float hi) { return pg8::cvt_pk_bf16(lo, hi); }
;     __device__ __forceinline__ void operator()(const pg8::f32x4 (&acc)[2][2][4][2], const pg8::Unit& u, int wr, int wc, int fr, int fq) const {
;     ...
;                         const pg8::f32x4 v0 = acc[ai][bj][m][0] * rs, v1 = acc[ai][bj][m][1] * rs;
;                         u32x4 w; w.x = pk2(v0[0], v0[1]); w.y = pk2(v0[2], v0[3]); w.z = pk2(v1[0], v1[1]); w.w = pk2(v1[2], v1[3]);
;                         if (vt_all || (vt_half && bj == 1)) {
;                             bf16_t* vp = vt + (size_t)(vrow0 + bj * 128) * S + row;
;                             vp[0 * (size_t)S] = (bf16_t)(w.x & 0xffffu); vp[1 * (size_t)S] = (bf16_t)(w.x >> 16); vp[2 * (size_t)S] = (bf16_t)(w.y & 0xffffu); vp[3 * (size_t)S] = (bf16_t)(w.y >> 16);
;                             vp[4 * (size_t)S] = (bf16_t)(w.z & 0xffffu); vp[5 * (size_t)S] = (bf16_t)(w.z >> 16); vp[6 * (size_t)S] = (bf16_t)(w.w & 0xffffu); vp[7 * (size_t)S] = (bf16_t)(w.w >> 16);
.LBB0_448:
	s_and_b64 vcc, exec, s[0:1]
	s_cbranch_vccz .LBB0_450
	ds_write_b128 v226, v[36:39]
	v_lshlrev_b64 v[40:41], 15, v[128:129]
	v_lshl_add_u64 v[40:41], s[6:7], 0, v[40:41]
	v_lshl_add_u64 v[40:41], v[250:251], 1, v[40:41]
	v_lshl_add_u64 v[40:41], v[248:249], 0, v[40:41]
	v_add_co_u32_e32 v42, vcc, 0x400000, v40
	s_nop 1
	v_addc_co_u32_e32 v43, vcc, 0, v41, vcc
	ds_read_b64_tr_b16 v[36:37], v227
	ds_read_b64_tr_b16 v[38:39], v227 offset:128
	s_waitcnt lgkmcnt(0)
	global_store_dwordx4 v[42:43], v[36:39], off offset:288
	s_nop 1

; __device__ __forceinline__ unsigned pk2(float lo, float hi) { return pg8::cvt_pk_bf16(lo, hi); }
;     __device__ __forceinline__ void operator()(const pg8::f32x4 (&acc)[2][2][4][2], const pg8::Unit& u, int wr, int wc, int fr, int fq) const {
;     ...
;                         const pg8::f32x4 v0 = acc[ai][bj][m][0] * rs, v1 = acc[ai][bj][m][1] * rs;
;                         u32x4 w; w.x = pk2(v0[0], v0[1]); w.y = pk2(v0[2], v0[3]); w.z = pk2(v1[0], v1[1]); w.w = pk2(v1[2], v1[3]);
;                         if (vt_all || (vt_half && bj == 1)) {
;                             bf16_t* vp = vt + (size_t)(vrow0 + bj * 128) * S + row;
;                             vp[0 * (size_t)S] = (bf16_t)(w.x & 0xffffu); vp[1 * (size_t)S] = (bf16_t)(w.x >> 16); vp[2 * (size_t)S] = (bf16_t)(w.y & 0xffffu); vp[3 * (size_t)S] = (bf16_t)(w.y >> 16);
;                             vp[4 * (size_t)S] = (bf16_t)(w.z & 0xffffu); vp[5 * (size_t)S] = (bf16_t)(w.z >> 16); vp[6 * (size_t)S] = (bf16_t)(w.w & 0xffffu); vp[7 * (size_t)S] = (bf16_t)(w.w >> 16);
.LBB0_459:
	ds_write_b128 v226, v[24:27]
	v_lshlrev_b64 v[28:29], 15, v[128:129]
	v_lshl_add_u64 v[28:29], s[6:7], 0, v[28:29]
	v_lshl_add_u64 v[28:29], v[250:251], 1, v[28:29]
	v_lshl_add_u64 v[28:29], v[248:249], 0, v[28:29]
	v_add_co_u32_e32 v30, vcc, 0x8000, v28
	ds_read_b64_tr_b16 v[24:25], v227
	ds_read_b64_tr_b16 v[26:27], v227 offset:128
	s_waitcnt lgkmcnt(0)
	global_store_dwordx4 v[28:29], v[24:27], off offset:320
	s_nop 1
	v_mov_b32_e32 v39, v38
	s_cmp_lt_i32 s57, 10
	s_cbranch_scc0 .LBB0_457

; __device__ __forceinline__ unsigned pk2(float lo, float hi) { return pg8::cvt_pk_bf16(lo, hi); }
;     __device__ __forceinline__ void operator()(const pg8::f32x4 (&acc)[2][2][4][2], const pg8::Unit& u, int wr, int wc, int fr, int fq) const {
;     ...
;                         const pg8::f32x4 v0 = acc[ai][bj][m][0] * rs, v1 = acc[ai][bj][m][1] * rs;
;                         u32x4 w; w.x = pk2(v0[0], v0[1]); w.y = pk2(v0[2], v0[3]); w.z = pk2(v1[0], v1[1]); w.w = pk2(v1[2], v1[3]);
;                         if (vt_all || (vt_half && bj == 1)) {
;                             bf16_t* vp = vt + (size_t)(vrow0 + bj * 128) * S + row;
;                             vp[0 * (size_t)S] = (bf16_t)(w.x & 0xffffu); vp[1 * (size_t)S] = (bf16_t)(w.x >> 16); vp[2 * (size_t)S] = (bf16_t)(w.y & 0xffffu); vp[3 * (size_t)S] = (bf16_t)(w.y >> 16);
;                             vp[4 * (size_t)S] = (bf16_t)(w.z & 0xffffu); vp[5 * (size_t)S] = (bf16_t)(w.z >> 16); vp[6 * (size_t)S] = (bf16_t)(w.w & 0xffffu); vp[7 * (size_t)S] = (bf16_t)(w.w >> 16);
.LBB0_465:
	s_and_b64 vcc, exec, s[0:1]
	s_cbranch_vccz .LBB0_467
	ds_write_b128 v226, v[16:19]
	v_lshlrev_b64 v[20:21], 15, v[128:129]
	v_lshl_add_u64 v[20:21], s[6:7], 0, v[20:21]
	v_lshl_add_u64 v[20:21], v[250:251], 1, v[20:21]
	v_lshl_add_u64 v[20:21], v[248:249], 0, v[20:21]
	v_add_co_u32_e32 v22, vcc, 0x400000, v20
	s_nop 1
	v_addc_co_u32_e32 v23, vcc, 0, v21, vcc
	ds_read_b64_tr_b16 v[16:17], v227
	ds_read_b64_tr_b16 v[18:19], v227 offset:128
	s_waitcnt lgkmcnt(0)
	global_store_dwordx4 v[22:23], v[16:19], off offset:320
	s_nop 1

; __device__ __forceinline__ unsigned pk2(float lo, float hi) { return pg8::cvt_pk_bf16(lo, hi); }
;     __device__ __forceinline__ void operator()(const pg8::f32x4 (&acc)[2][2][4][2], const pg8::Unit& u, int wr, int wc, int fr, int fq) const {
;     ...
;                         const pg8::f32x4 v0 = acc[ai][bj][m][0] * rs, v1 = acc[ai][bj][m][1] * rs;
;                         u32x4 w; w.x = pk2(v0[0], v0[1]); w.y = pk2(v0[2], v0[3]); w.z = pk2(v1[0], v1[1]); w.w = pk2(v1[2], v1[3]);
;                         if (vt_all || (vt_half && bj == 1)) {
;                             bf16_t* vp = vt + (size_t)(vrow0 + bj * 128) * S + row;
;                             vp[0 * (size_t)S] = (bf16_t)(w.x & 0xffffu); vp[1 * (size_t)S] = (bf16_t)(w.x >> 16); vp[2 * (size_t)S] = (bf16_t)(w.y & 0xffffu); vp[3 * (size_t)S] = (bf16_t)(w.y >> 16);
;                             vp[4 * (size_t)S] = (bf16_t)(w.z & 0xffffu); vp[5 * (size_t)S] = (bf16_t)(w.z >> 16); vp[6 * (size_t)S] = (bf16_t)(w.w & 0xffffu); vp[7 * (size_t)S] = (bf16_t)(w.w >> 16);
.LBB0_476:
	ds_write_b128 v226, v[8:11]
	v_lshlrev_b64 v[12:13], 15, v[128:129]
	v_lshl_add_u64 v[12:13], s[6:7], 0, v[12:13]
	v_lshl_add_u64 v[12:13], v[250:251], 1, v[12:13]
	v_lshl_add_u64 v[12:13], v[248:249], 0, v[12:13]
	v_add_co_u32_e32 v14, vcc, 0x8000, v12
	ds_read_b64_tr_b16 v[8:9], v227
	ds_read_b64_tr_b16 v[10:11], v227 offset:128
	s_waitcnt lgkmcnt(0)
	global_store_dwordx4 v[12:13], v[8:11], off offset:352
	s_nop 1
	v_mov_b32_e32 v19, v18
	s_cmp_lt_i32 s57, 10
	s_cbranch_scc0 .LBB0_474

; __device__ __forceinline__ unsigned pk2(float lo, float hi) { return pg8::cvt_pk_bf16(lo, hi); }
;     __device__ __forceinline__ void operator()(const pg8::f32x4 (&acc)[2][2][4][2], const pg8::Unit& u, int wr, int wc, int fr, int fq) const {
;     ...
;                         const pg8::f32x4 v0 = acc[ai][bj][m][0] * rs, v1 = acc[ai][bj][m][1] * rs;
;                         u32x4 w; w.x = pk2(v0[0], v0[1]); w.y = pk2(v0[2], v0[3]); w.z = pk2(v1[0], v1[1]); w.w = pk2(v1[2], v1[3]);
;                         if (vt_all || (vt_half && bj == 1)) {
;                             bf16_t* vp = vt + (size_t)(vrow0 + bj * 128) * S + row;
;                             vp[0 * (size_t)S] = (bf16_t)(w.x & 0xffffu); vp[1 * (size_t)S] = (bf16_t)(w.x >> 16); vp[2 * (size_t)S] = (bf16_t)(w.y & 0xffffu); vp[3 * (size_t)S] = (bf16_t)(w.y >> 16);
;                             vp[4 * (size_t)S] = (bf16_t)(w.z & 0xffffu); vp[5 * (size_t)S] = (bf16_t)(w.z >> 16); vp[6 * (size_t)S] = (bf16_t)(w.w & 0xffffu); vp[7 * (size_t)S] = (bf16_t)(w.w >> 16);
.LBB0_483:
	s_and_b64 vcc, exec, s[0:1]
	s_cbranch_vccz .LBB0_485
	ds_write_b128 v226, v[0:3]
	v_lshlrev_b64 v[4:5], 15, v[128:129]
	v_lshl_add_u64 v[4:5], s[6:7], 0, v[4:5]
	v_lshl_add_u64 v[4:5], v[250:251], 1, v[4:5]
	v_lshl_add_u64 v[4:5], v[248:249], 0, v[4:5]
	v_add_co_u32_e32 v6, vcc, 0x400000, v4
	s_nop 1
	v_addc_co_u32_e32 v7, vcc, 0, v5, vcc
	ds_read_b64_tr_b16 v[0:1], v227
	ds_read_b64_tr_b16 v[2:3], v227 offset:128
	s_waitcnt lgkmcnt(0)
	global_store_dwordx4 v[6:7], v[0:3], off offset:352
	s_nop 1
